# P6 <4,2> and P1 <2,2> sample-row GEMM operand loads with contiguous lane order + ds_bpermute
# speedup vs baseline: 1.0050x; 1.0018x over previous
.LBB0_322:
	s_or_b64 exec, exec, s[10:11]
	v_and_b32_e32 v102, 63, v204
	v_lshrrev_b32_e32 v103, 2, v102
	v_and_b32_e32 v104, 15, v102
	v_lshlrev_b32_e32 v100, 2, v104
	v_lshrrev_b32_e32 v105, 4, v102
	v_add_u32_e32 v100, v100, v105
	v_lshlrev_b32_e32 v100, 2, v100
	v_sub_u32_e32 v103, v103, v104
	v_lshlrev_b32_e32 v103, 11, v103
	v_and_b32_e32 v104, 3, v102
	v_lshlrev_b32_e32 v104, 4, v104
	v_and_b32_e32 v105, 48, v102
	v_sub_u32_e32 v104, v104, v105
	v_add_u32_e32 v102, v103, v104
	v_ashrrev_i32_e32 v103, 31, v102
	s_lshl_b32 s13, s13, 5
	v_or_b32_e32 v10, s13, v18
	v_ashrrev_i32_e32 v11, 31, v10
	v_lshlrev_b64 v[10:11], 11, v[10:11]
	s_add_i32 s12, s12, s9
	v_lshl_add_u64 v[54:55], v[8:9], 0, v[10:11]
	v_lshl_add_u64 v[54:55], v[54:55], 0, v[102:103]
	v_add_u32_e32 v0, s12, v18
	s_waitcnt lgkmcnt(0)
	global_load_dwordx4 v[10:13], v[54:55], off
	v_ashrrev_i32_e32 v1, 31, v0
	v_lshlrev_b64 v[0:1], 11, v[0:1]
	v_lshl_add_u64 v[0:1], v[6:7], 0, v[0:1]
	v_lshl_add_u64 v[0:1], v[0:1], 0, v[102:103]
	global_load_dwordx4 v[14:17], v[0:1], off
	v_add_co_u32_e32 v62, vcc, 0x8000, v0
	s_waitcnt vmcnt(0)
	ds_bpermute_b32 v10, v100, v10
	ds_bpermute_b32 v11, v100, v11
	ds_bpermute_b32 v12, v100, v12
	ds_bpermute_b32 v13, v100, v13
	ds_bpermute_b32 v14, v100, v14
	ds_bpermute_b32 v15, v100, v15
	ds_bpermute_b32 v16, v100, v16
	ds_bpermute_b32 v17, v100, v17
	s_waitcnt lgkmcnt(0)
	v_mfma_f32_16x16x32_bf16 v[38:41], v[10:13], v[14:17], 0
	v_addc_co_u32_e32 v63, vcc, 0, v1, vcc
	global_load_dwordx4 v[26:29], v[62:63], off
	global_load_dwordx4 v[30:33], v[0:1], off offset:64
	global_load_dwordx4 v[34:37], v[54:55], off offset:64
	s_and_saveexec_b64 s[10:11], s[4:5]
	v_ffbh_u32_e32 v122, v121
	v_min_u32_e32 v122, 32, v122
	v_lshlrev_b64 v[120:121], v122, v[120:121]
	v_min_u32_e32 v120, 1, v120
	v_or_b32_e32 v120, v121, v120
	v_cvt_f32_u32_e32 v120, v120
	v_sub_u32_e32 v121, 32, v122
	v_ldexp_f32 v120, v120, v121
	v_fmamk_f32 v120, v120, 0x30800000, v24
	v_mul_f32_e32 v121, 0x4b800000, v120
	v_cmp_gt_f32_e32 vcc, s20, v120
	s_nop 1
	v_cndmask_b32_e32 v120, v120, v121, vcc
	v_rsq_f32_e32 v120, v120
	s_nop 0
	v_mul_f32_e32 v121, 0x45800000, v120
	v_cndmask_b32_e32 v2, v120, v121, vcc
	s_or_b64 exec, exec, s[10:11]
	v_add_co_u32_e32 v64, vcc, 0x8000, v54
	s_waitcnt vmcnt(2)
	ds_bpermute_b32 v26, v100, v26
	ds_bpermute_b32 v27, v100, v27
	ds_bpermute_b32 v28, v100, v28
	ds_bpermute_b32 v29, v100, v29
	s_waitcnt lgkmcnt(0)
	v_mfma_f32_16x16x32_bf16 v[10:13], v[10:13], v[26:29], 0
	v_addc_co_u32_e32 v65, vcc, 0, v55, vcc
	global_load_dwordx4 v[42:45], v[64:65], off
	global_load_dwordx4 v[46:49], v[62:63], off offset:64
	global_load_dwordx4 v[50:53], v[64:65], off offset:64
	s_waitcnt vmcnt(2)
	ds_bpermute_b32 v42, v100, v42
	ds_bpermute_b32 v43, v100, v43
	ds_bpermute_b32 v44, v100, v44
	ds_bpermute_b32 v45, v100, v45
	s_waitcnt lgkmcnt(0)
	v_mfma_f32_16x16x32_bf16 v[14:17], v[42:45], v[14:17], 0
	ds_bpermute_b32 v34, v100, v34
	ds_bpermute_b32 v35, v100, v35
	ds_bpermute_b32 v36, v100, v36
	ds_bpermute_b32 v37, v100, v37
	ds_bpermute_b32 v30, v100, v30
	ds_bpermute_b32 v31, v100, v31
	ds_bpermute_b32 v32, v100, v32
	ds_bpermute_b32 v33, v100, v33
	s_waitcnt lgkmcnt(0)
	v_mfma_f32_16x16x32_bf16 v[38:41], v[34:37], v[30:33], v[38:41]
	s_waitcnt vmcnt(1)
	ds_bpermute_b32 v46, v100, v46
	ds_bpermute_b32 v47, v100, v47
	ds_bpermute_b32 v48, v100, v48
	ds_bpermute_b32 v49, v100, v49
	s_waitcnt lgkmcnt(0)
	v_mfma_f32_16x16x32_bf16 v[10:13], v[34:37], v[46:49], v[10:13]
	global_load_dwordx4 v[34:37], v[54:55], off offset:128
	v_mfma_f32_16x16x32_bf16 v[26:29], v[42:45], v[26:29], 0
	s_waitcnt vmcnt(1)
	ds_bpermute_b32 v50, v100, v50
	ds_bpermute_b32 v51, v100, v51
	ds_bpermute_b32 v52, v100, v52
	ds_bpermute_b32 v53, v100, v53
	s_waitcnt lgkmcnt(0)
	v_mfma_f32_16x16x32_bf16 v[14:17], v[50:53], v[30:33], v[14:17]
	global_load_dwordx4 v[30:33], v[0:1], off offset:128
	v_mfma_f32_16x16x32_bf16 v[26:29], v[50:53], v[46:49], v[26:29]
	global_load_dwordx4 v[42:45], v[62:63], off offset:128
	global_load_dwordx4 v[46:49], v[0:1], off offset:192
	global_load_dwordx4 v[50:53], v[54:55], off offset:192
	s_nop 0
	global_load_dwordx4 v[54:57], v[64:65], off offset:128
	global_load_dwordx4 v[58:61], v[62:63], off offset:192
	s_waitcnt vmcnt(5)
	ds_bpermute_b32 v34, v100, v34
	ds_bpermute_b32 v35, v100, v35
	ds_bpermute_b32 v36, v100, v36
	ds_bpermute_b32 v37, v100, v37
	ds_bpermute_b32 v30, v100, v30
	ds_bpermute_b32 v31, v100, v31
	ds_bpermute_b32 v32, v100, v32
	ds_bpermute_b32 v33, v100, v33
	s_waitcnt lgkmcnt(0)
	v_mfma_f32_16x16x32_bf16 v[38:41], v[34:37], v[30:33], v[38:41]
	s_waitcnt vmcnt(4)
	ds_bpermute_b32 v42, v100, v42
	ds_bpermute_b32 v43, v100, v43
	ds_bpermute_b32 v44, v100, v44
	ds_bpermute_b32 v45, v100, v45
	s_waitcnt lgkmcnt(0)
	v_mfma_f32_16x16x32_bf16 v[10:13], v[34:37], v[42:45], v[10:13]
	global_load_dwordx4 v[34:37], v[64:65], off offset:192
	s_waitcnt vmcnt(2)
	ds_bpermute_b32 v54, v100, v54
	ds_bpermute_b32 v55, v100, v55
	ds_bpermute_b32 v56, v100, v56
	ds_bpermute_b32 v57, v100, v57
	s_waitcnt lgkmcnt(0)
	v_mfma_f32_16x16x32_bf16 v[14:17], v[54:57], v[30:33], v[14:17]
	v_mfma_f32_16x16x32_bf16 v[26:29], v[54:57], v[42:45], v[26:29]
	ds_bpermute_b32 v50, v100, v50
	ds_bpermute_b32 v51, v100, v51
	ds_bpermute_b32 v52, v100, v52
	ds_bpermute_b32 v53, v100, v53
	ds_bpermute_b32 v46, v100, v46
	ds_bpermute_b32 v47, v100, v47
	ds_bpermute_b32 v48, v100, v48
	ds_bpermute_b32 v49, v100, v49
	s_waitcnt lgkmcnt(0)
	v_mfma_f32_16x16x32_bf16 v[30:33], v[50:53], v[46:49], v[38:41]
	s_waitcnt vmcnt(1)
	ds_bpermute_b32 v58, v100, v58
	ds_bpermute_b32 v59, v100, v59
	ds_bpermute_b32 v60, v100, v60
	ds_bpermute_b32 v61, v100, v61
	s_waitcnt lgkmcnt(0)
	v_mfma_f32_16x16x32_bf16 v[10:13], v[50:53], v[58:61], v[10:13]
	s_waitcnt vmcnt(0)
	ds_bpermute_b32 v34, v100, v34
	ds_bpermute_b32 v35, v100, v35
	ds_bpermute_b32 v36, v100, v36
	ds_bpermute_b32 v37, v100, v37
	s_waitcnt lgkmcnt(0)
	v_mfma_f32_16x16x32_bf16 v[14:17], v[34:37], v[46:49], v[14:17]
	v_mfma_f32_16x16x32_bf16 v[26:29], v[34:37], v[58:61], v[26:29]
	s_nop 2
	ds_write_b128 v25, v[30:33]
	s_nop 0
	ds_write_b128 v25, v[10:13] offset:2048
	s_nop 0
	ds_write_b128 v25, v[14:17] offset:1024
	ds_write_b128 v25, v[26:29] offset:3072
	s_waitcnt lgkmcnt(0)
	s_barrier
	s_and_saveexec_b64 s[10:11], s[4:5]
	s_cbranch_execz .LBB0_319
	ds_read_b128 v[14:17], v20
	ds_read_b128 v[26:29], v21 offset:4096
	ds_read_b128 v[30:33], v21 offset:8192
	ds_read_b128 v[34:37], v21 offset:12288
	v_add_u32_e32 v0, s12, v23
	v_add_u32_e32 v12, 0x4000, v0
	s_waitcnt lgkmcnt(2)
	v_pk_add_f32 v[0:1], v[16:17], v[28:29]
	v_pk_add_f32 v[26:27], v[14:15], v[26:27]
	ds_read_b128 v[14:17], v21 offset:16384
	s_waitcnt lgkmcnt(2)
	v_pk_add_f32 v[26:27], v[26:27], v[30:31]
	v_pk_add_f32 v[0:1], v[0:1], v[32:33]
	s_waitcnt lgkmcnt(1)
	v_pk_add_f32 v[34:35], v[26:27], v[34:35]
	ds_read_b128 v[26:29], v21 offset:20480
	v_pk_add_f32 v[0:1], v[0:1], v[36:37]
	ds_read_b128 v[30:33], v21 offset:24576
	s_waitcnt lgkmcnt(2)
	v_pk_add_f32 v[0:1], v[0:1], v[16:17]
	v_pk_add_f32 v[34:35], v[34:35], v[14:15]
	ds_read_b128 v[14:17], v21 offset:28672
	s_waitcnt lgkmcnt(2)
	v_pk_add_f32 v[0:1], v[0:1], v[28:29]
	v_pk_add_f32 v[26:27], v[34:35], v[26:27]
	s_waitcnt lgkmcnt(1)
	v_pk_add_f32 v[0:1], v[0:1], v[32:33]
	v_pk_add_f32 v[26:27], v[26:27], v[30:31]
	s_waitcnt lgkmcnt(0)
	v_pk_add_f32 v[16:17], v[0:1], v[16:17]
	v_pk_add_f32 v[0:1], v[26:27], v[14:15]
	v_add_u32_e32 v10, s13, v22
	v_ashrrev_i32_e32 v13, 31, v12
	v_pk_mul_f32 v[0:1], v[2:3], v[0:1] op_sel_hi:[0,1]
	v_pk_mul_f32 v[2:3], v[2:3], v[16:17] op_sel_hi:[0,1]
	v_lshlrev_b64 v[38:39], 11, v[12:13]
	v_pk_mul_f32 v[16:17], v[0:1], s[8:9] op_sel_hi:[1,0]
	v_pk_mul_f32 v[26:27], v[2:3], s[8:9] op_sel_hi:[1,0]
	v_cmp_gt_i32_e32 vcc, s21, v10
	v_ashrrev_i32_e32 v11, 31, v10
	v_lshl_add_u64 v[14:15], s[68:69], 0, v[38:39]
	v_cndmask_b32_e32 v4, v27, v3, vcc
	v_cndmask_b32_e32 v13, v26, v2, vcc
	v_cndmask_b32_e32 v17, v17, v1, vcc
	v_cndmask_b32_e32 v16, v16, v0, vcc
	v_lshl_add_u64 v[14:15], v[10:11], 1, v[14:15]
	v_cvt_pk_bf16_f32 v16, v16, v17
	v_cvt_pk_bf16_f32 v17, v13, v4
	global_store_dwordx2 v[14:15], v[16:17], off
	s_and_b64 exec, exec, vcc
	s_cbranch_execz .LBB0_319
	v_add_u32_e32 v4, s12, v19
	v_cmp_lt_i32_e32 vcc, s22, v12
	s_mov_b64 s[12:13], 0
	s_and_saveexec_b64 s[14:15], vcc
	s_xor_b64 s[14:15], exec, s[14:15]
	s_cbranch_execz .LBB0_327
	v_lshrrev_b32_e32 v4, 5, v4
	v_and_b32_e32 v12, 31, v12
	v_mul_lo_u32 v4, v4, 15
	v_add3_u32 v4, v4, v12, s23
	v_cmp_lt_u32_e32 vcc, 16, v12
	s_and_b64 s[12:13], vcc, exec
	v_mov_b64_e32 v[14:15], v[4:5]
	s_or_saveexec_b64 s[14:15], s[14:15]
	v_mov_b64_e32 v[16:17], 0x850f000
	s_xor_b64 exec, exec, s[14:15]
	s_cbranch_execnz .LBB0_328

.LBB0_1278:
	s_or_b64 exec, exec, s[36:37]
	v_and_b32_e32 v132, 63, v204
	v_lshrrev_b32_e32 v133, 2, v132
	v_and_b32_e32 v134, 15, v132
	v_lshlrev_b32_e32 v130, 2, v134
	v_lshrrev_b32_e32 v135, 4, v132
	v_add_u32_e32 v130, v130, v135
	v_lshlrev_b32_e32 v130, 2, v130
	v_sub_u32_e32 v133, v133, v134
	v_lshlrev_b32_e32 v133, 11, v133
	v_and_b32_e32 v134, 3, v132
	v_lshlrev_b32_e32 v134, 4, v134
	v_and_b32_e32 v135, 48, v132
	v_sub_u32_e32 v134, v134, v135
	v_add_u32_e32 v132, v133, v134
	v_ashrrev_i32_e32 v133, 31, v132
	v_add_u32_e32 v2, s22, v23
	v_ashrrev_i32_e32 v3, 31, v2
	v_lshlrev_b64 v[2:3], 11, v[2:3]
	v_lshl_add_u64 v[80:81], v[6:7], 0, v[2:3]
	v_lshl_add_u64 v[80:81], v[80:81], 0, v[132:133]
	v_add_co_u32_e32 v84, vcc, 0x8000, v80
	s_lshl_b32 s21, s21, 5
	s_nop 0
	v_addc_co_u32_e32 v85, vcc, 0, v81, vcc
	v_or_b32_e32 v2, s21, v16
	v_add_co_u32_e32 v86, vcc, 0x10000, v80
	v_ashrrev_i32_e32 v3, 31, v2
	s_nop 0
	v_addc_co_u32_e32 v87, vcc, 0, v81, vcc
	v_lshlrev_b64 v[2:3], 11, v[2:3]
	v_add_co_u32_e32 v92, vcc, 0x18000, v80
	v_lshl_add_u64 v[82:83], v[8:9], 0, v[2:3]
	v_lshl_add_u64 v[82:83], v[82:83], 0, v[132:133]
	s_nop 0
	v_addc_co_u32_e32 v93, vcc, 0, v81, vcc
	v_add_co_u32_e32 v96, vcc, s50, v82
	global_load_dwordx4 v[2:5], v[80:81], off
	global_load_dwordx4 v[24:27], v[82:83], off
	v_addc_co_u32_e32 v97, vcc, 0, v83, vcc
	global_load_dwordx4 v[28:31], v[84:85], off
	global_load_dwordx4 v[32:35], v[86:87], off
	global_load_dwordx4 v[36:39], v[92:93], off
	global_load_dwordx4 v[40:43], v[80:81], off offset:64
	global_load_dwordx4 v[44:47], v[82:83], off offset:64
	global_load_dwordx4 v[48:51], v[84:85], off offset:64
	global_load_dwordx4 v[56:59], v[86:87], off offset:64
	global_load_dwordx4 v[68:71], v[96:97], off
	global_load_dwordx4 v[72:75], v[92:93], off offset:64
	global_load_dwordx4 v[76:79], v[96:97], off offset:64
	v_add_u32_e32 v13, s19, v18
	s_waitcnt vmcnt(0)
	s_and_saveexec_b64 s[36:37], s[0:1]
	v_ffbh_u32_e32 v122, v121
	v_min_u32_e32 v122, 32, v122
	v_lshlrev_b64 v[120:121], v122, v[120:121]
	v_min_u32_e32 v120, 1, v120
	v_or_b32_e32 v120, v121, v120
	v_cvt_f32_u32_e32 v120, v120
	v_sub_u32_e32 v121, 32, v122
	v_ldexp_f32 v120, v120, v121
	v_fmamk_f32 v120, v120, 0x30800000, v207
	v_mul_f32_e32 v121, 0x4b800000, v120
	v_cmp_gt_f32_e32 vcc, s16, v120
	s_nop 1
	v_cndmask_b32_e32 v120, v120, v121, vcc
	v_rsq_f32_e32 v120, v120
	s_nop 0
	v_mul_f32_e32 v121, 0x45800000, v120
	v_cndmask_b32_e32 v0, v120, v121, vcc
	s_or_b64 exec, exec, s[36:37]
	ds_bpermute_b32 v24, v130, v24
	ds_bpermute_b32 v25, v130, v25
	ds_bpermute_b32 v26, v130, v26
	ds_bpermute_b32 v27, v130, v27
	ds_bpermute_b32 v2, v130, v2
	ds_bpermute_b32 v3, v130, v3
	ds_bpermute_b32 v4, v130, v4
	ds_bpermute_b32 v5, v130, v5
	s_waitcnt lgkmcnt(0)
	v_mfma_f32_16x16x32_bf16 v[52:55], v[24:27], v[2:5], 0
	ds_bpermute_b32 v68, v130, v68
	ds_bpermute_b32 v69, v130, v69
	ds_bpermute_b32 v70, v130, v70
	ds_bpermute_b32 v71, v130, v71
	s_waitcnt lgkmcnt(0)
	v_mfma_f32_16x16x32_bf16 v[2:5], v[68:71], v[2:5], 0
	ds_bpermute_b32 v28, v130, v28
	ds_bpermute_b32 v29, v130, v29
	ds_bpermute_b32 v30, v130, v30
	ds_bpermute_b32 v31, v130, v31
	s_waitcnt lgkmcnt(0)
	v_mfma_f32_16x16x32_bf16 v[60:63], v[24:27], v[28:31], 0
	ds_bpermute_b32 v32, v130, v32
	ds_bpermute_b32 v33, v130, v33
	ds_bpermute_b32 v34, v130, v34
	ds_bpermute_b32 v35, v130, v35
	s_waitcnt lgkmcnt(0)
	v_mfma_f32_16x16x32_bf16 v[64:67], v[24:27], v[32:35], 0
	ds_bpermute_b32 v36, v130, v36
	ds_bpermute_b32 v37, v130, v37
	ds_bpermute_b32 v38, v130, v38
	ds_bpermute_b32 v39, v130, v39
	s_waitcnt lgkmcnt(0)
	v_mfma_f32_16x16x32_bf16 v[24:27], v[24:27], v[36:39], 0
	ds_bpermute_b32 v44, v130, v44
	ds_bpermute_b32 v45, v130, v45
	ds_bpermute_b32 v46, v130, v46
	ds_bpermute_b32 v47, v130, v47
	ds_bpermute_b32 v40, v130, v40
	ds_bpermute_b32 v41, v130, v41
	ds_bpermute_b32 v42, v130, v42
	ds_bpermute_b32 v43, v130, v43
	s_waitcnt lgkmcnt(0)
	v_mfma_f32_16x16x32_bf16 v[52:55], v[44:47], v[40:43], v[52:55]
	ds_bpermute_b32 v76, v130, v76
	ds_bpermute_b32 v77, v130, v77
	ds_bpermute_b32 v78, v130, v78
	ds_bpermute_b32 v79, v130, v79
	s_waitcnt lgkmcnt(0)
	v_mfma_f32_16x16x32_bf16 v[2:5], v[76:79], v[40:43], v[2:5]
	global_load_dwordx4 v[40:43], v[82:83], off offset:128
	v_mfma_f32_16x16x32_bf16 v[28:31], v[68:71], v[28:31], 0
	v_mfma_f32_16x16x32_bf16 v[32:35], v[68:71], v[32:35], 0
	v_mfma_f32_16x16x32_bf16 v[36:39], v[68:71], v[36:39], 0
	ds_bpermute_b32 v48, v130, v48
	ds_bpermute_b32 v49, v130, v49
	ds_bpermute_b32 v50, v130, v50
	ds_bpermute_b32 v51, v130, v51
	s_waitcnt lgkmcnt(0)
	v_mfma_f32_16x16x32_bf16 v[60:63], v[44:47], v[48:51], v[60:63]
	ds_bpermute_b32 v56, v130, v56
	ds_bpermute_b32 v57, v130, v57
	ds_bpermute_b32 v58, v130, v58
	ds_bpermute_b32 v59, v130, v59
	s_waitcnt lgkmcnt(0)
	v_mfma_f32_16x16x32_bf16 v[64:67], v[44:47], v[56:59], v[64:67]
	ds_bpermute_b32 v72, v130, v72
	ds_bpermute_b32 v73, v130, v73
	ds_bpermute_b32 v74, v130, v74
	ds_bpermute_b32 v75, v130, v75
	s_waitcnt lgkmcnt(0)
	v_mfma_f32_16x16x32_bf16 v[24:27], v[44:47], v[72:75], v[24:27]
	global_load_dwordx4 v[44:47], v[80:81], off offset:128
	v_mfma_f32_16x16x32_bf16 v[28:31], v[76:79], v[48:51], v[28:31]
	v_mfma_f32_16x16x32_bf16 v[32:35], v[76:79], v[56:59], v[32:35]
	global_load_dwordx4 v[48:51], v[84:85], off offset:128
	global_load_dwordx4 v[56:59], v[80:81], off offset:192
	global_load_dwordx4 v[68:71], v[82:83], off offset:192
	v_mfma_f32_16x16x32_bf16 v[36:39], v[76:79], v[72:75], v[36:39]
	global_load_dwordx4 v[72:75], v[86:87], off offset:128
	global_load_dwordx4 v[76:79], v[84:85], off offset:192
	global_load_dwordx4 v[80:83], v[92:93], off offset:128
	s_nop 0
	global_load_dwordx4 v[84:87], v[86:87], off offset:192
	s_nop 0
	global_load_dwordx4 v[88:91], v[96:97], off offset:128
	s_nop 0
	global_load_dwordx4 v[92:95], v[92:93], off offset:192
	s_waitcnt vmcnt(1)
	ds_bpermute_b32 v88, v130, v88
	ds_bpermute_b32 v89, v130, v89
	ds_bpermute_b32 v90, v130, v90
	ds_bpermute_b32 v91, v130, v91
	ds_bpermute_b32 v48, v130, v48
	ds_bpermute_b32 v49, v130, v49
	ds_bpermute_b32 v50, v130, v50
	ds_bpermute_b32 v51, v130, v51
	s_waitcnt lgkmcnt(0)
	v_mfma_f32_16x16x32_bf16 v[28:31], v[88:91], v[48:51], v[28:31]
	ds_bpermute_b32 v40, v130, v40
	ds_bpermute_b32 v41, v130, v41
	ds_bpermute_b32 v42, v130, v42
	ds_bpermute_b32 v43, v130, v43
	ds_bpermute_b32 v44, v130, v44
	ds_bpermute_b32 v45, v130, v45
	ds_bpermute_b32 v46, v130, v46
	ds_bpermute_b32 v47, v130, v47
	s_waitcnt lgkmcnt(0)
	v_mfma_f32_16x16x32_bf16 v[52:55], v[40:43], v[44:47], v[52:55]
	v_mfma_f32_16x16x32_bf16 v[60:63], v[40:43], v[48:51], v[60:63]
	ds_bpermute_b32 v72, v130, v72
	ds_bpermute_b32 v73, v130, v73
	ds_bpermute_b32 v74, v130, v74
	ds_bpermute_b32 v75, v130, v75
	s_waitcnt lgkmcnt(0)
	v_mfma_f32_16x16x32_bf16 v[64:67], v[40:43], v[72:75], v[64:67]
	ds_bpermute_b32 v80, v130, v80
	ds_bpermute_b32 v81, v130, v81
	ds_bpermute_b32 v82, v130, v82
	ds_bpermute_b32 v83, v130, v83
	s_waitcnt lgkmcnt(0)
	v_mfma_f32_16x16x32_bf16 v[24:27], v[40:43], v[80:83], v[24:27]
	global_load_dwordx4 v[40:43], v[96:97], off offset:192
	v_mfma_f32_16x16x32_bf16 v[2:5], v[88:91], v[44:47], v[2:5]
	v_mfma_f32_16x16x32_bf16 v[32:35], v[88:91], v[72:75], v[32:35]
	ds_bpermute_b32 v68, v130, v68
	ds_bpermute_b32 v69, v130, v69
	ds_bpermute_b32 v70, v130, v70
	ds_bpermute_b32 v71, v130, v71
	ds_bpermute_b32 v56, v130, v56
	ds_bpermute_b32 v57, v130, v57
	ds_bpermute_b32 v58, v130, v58
	ds_bpermute_b32 v59, v130, v59
	s_waitcnt lgkmcnt(0)
	v_mfma_f32_16x16x32_bf16 v[44:47], v[68:71], v[56:59], v[52:55]
	s_waitcnt vmcnt(0)
	ds_bpermute_b32 v40, v130, v40
	ds_bpermute_b32 v41, v130, v41
	ds_bpermute_b32 v42, v130, v42
	ds_bpermute_b32 v43, v130, v43
	s_waitcnt lgkmcnt(0)
	v_mfma_f32_16x16x32_bf16 v[2:5], v[40:43], v[56:59], v[2:5]
	s_nop 5
	ds_write_b128 v13, v[44:47]
	ds_bpermute_b32 v76, v130, v76
	ds_bpermute_b32 v77, v130, v77
	ds_bpermute_b32 v78, v130, v78
	ds_bpermute_b32 v79, v130, v79
	s_waitcnt lgkmcnt(0)
	v_mfma_f32_16x16x32_bf16 v[48:51], v[68:71], v[76:79], v[60:63]
	v_mfma_f32_16x16x32_bf16 v[36:39], v[88:91], v[80:83], v[36:39]
	v_mfma_f32_16x16x32_bf16 v[28:31], v[40:43], v[76:79], v[28:31]
	ds_write_b128 v13, v[2:5] offset:1024
	s_nop 4
	ds_write_b128 v13, v[48:51] offset:2048
	s_nop 0
	ds_write_b128 v13, v[28:31] offset:3072
	ds_bpermute_b32 v84, v130, v84
	ds_bpermute_b32 v85, v130, v85
	ds_bpermute_b32 v86, v130, v86
	ds_bpermute_b32 v87, v130, v87
	s_waitcnt lgkmcnt(0)
	v_mfma_f32_16x16x32_bf16 v[52:55], v[68:71], v[84:87], v[64:67]
	v_mfma_f32_16x16x32_bf16 v[32:35], v[40:43], v[84:87], v[32:35]
	ds_bpermute_b32 v92, v130, v92
	ds_bpermute_b32 v93, v130, v93
	ds_bpermute_b32 v94, v130, v94
	ds_bpermute_b32 v95, v130, v95
	s_waitcnt lgkmcnt(0)
	v_mfma_f32_16x16x32_bf16 v[2:5], v[68:71], v[92:95], v[24:27]
	s_nop 5
	ds_write_b128 v13, v[52:55] offset:4096
	ds_write_b128 v13, v[32:35] offset:5120
	ds_write_b128 v13, v[2:5] offset:6144
	v_mfma_f32_16x16x32_bf16 v[2:5], v[40:43], v[92:95], v[36:39]
	s_nop 7
	ds_write_b128 v13, v[2:5] offset:7168
	s_waitcnt lgkmcnt(0)
	s_barrier
	s_and_saveexec_b64 s[36:37], s[0:1]
	s_cbranch_execz .LBB0_1275
	ds_read_b128 v[2:5], v19
	ds_read_b128 v[26:29], v20 offset:8192
	v_add_u32_e32 v24, s21, v21
	v_or_b32_e32 v14, v24, v22
	s_movk_i32 s12, 0x3ff
	v_cmp_lt_i32_e32 vcc, s12, v14
	s_waitcnt lgkmcnt(0)
	v_pk_add_f32 v[28:29], v[4:5], v[28:29]
	v_pk_add_f32 v[26:27], v[2:3], v[26:27]
	ds_read_b128 v[2:5], v20 offset:16384
	s_waitcnt lgkmcnt(0)
	v_pk_add_f32 v[28:29], v[28:29], v[4:5]
	v_pk_add_f32 v[26:27], v[26:27], v[2:3]
	ds_read_b128 v[2:5], v20 offset:24576
	s_waitcnt lgkmcnt(0)
	v_pk_add_f32 v[28:29], v[28:29], v[4:5]
	v_pk_add_f32 v[26:27], v[26:27], v[2:3]
	ds_read_b128 v[2:5], v20 offset:32768
	s_waitcnt lgkmcnt(0)
	v_pk_add_f32 v[28:29], v[28:29], v[4:5]
	v_pk_add_f32 v[26:27], v[26:27], v[2:3]
	ds_read_b128 v[2:5], v20 offset:40960
	s_waitcnt lgkmcnt(0)
	v_pk_add_f32 v[28:29], v[28:29], v[4:5]
	v_pk_add_f32 v[26:27], v[26:27], v[2:3]
	ds_read_b128 v[2:5], v20 offset:49152
	s_waitcnt lgkmcnt(0)
	v_pk_add_f32 v[28:29], v[28:29], v[4:5]
	v_pk_add_f32 v[26:27], v[26:27], v[2:3]
	ds_read_b128 v[2:5], v20 offset:57344
	s_waitcnt lgkmcnt(0)
	v_pk_add_f32 v[4:5], v[28:29], v[4:5]
	v_pk_add_f32 v[2:3], v[26:27], v[2:3]
	v_pk_mul_f32 v[4:5], v[0:1], v[4:5] op_sel_hi:[0,1]
	v_pk_mul_f32 v[2:3], v[0:1], v[2:3] op_sel_hi:[0,1]
	s_and_saveexec_b64 s[22:23], vcc
	s_xor_b64 s[40:41], exec, s[22:23]
	s_cbranch_execz .LBB0_1285
	s_movk_i32 s21, 0x3fff
	v_cmp_lt_i32_e64 s[42:43], s21, v12
	s_movk_i32 s21, 0x5ff
	v_cmp_lt_u32_e32 vcc, s21, v24
	v_mov_b32_e32 v0, 0x2152c00
	v_mov_b32_e32 v24, 0x2172c00
	s_movk_i32 s12, 0x4000
	v_cndmask_b32_e32 v0, v0, v24, vcc
	v_cndmask_b32_e32 v24, v211, v221, vcc
	v_cmp_gt_i32_e64 s[38:39], s12, v12
	v_cndmask_b32_e64 v12, v12, v15, s[42:43]
	v_cndmask_b32_e64 v0, v24, v0, s[42:43]
	v_ashrrev_i32_e32 v13, 31, v12
	v_lshlrev_b32_e32 v0, 2, v0
	v_and_b32_e32 v14, 0x1fc, v14
	v_lshl_add_u64 v[24:25], s[52:53], 0, v[0:1]
	v_lshlrev_b64 v[26:27], 11, v[12:13]
	v_lshl_add_u64 v[24:25], v[24:25], 0, v[26:27]
	v_lshlrev_b32_e32 v0, 2, v14
	v_lshl_add_u64 v[24:25], v[24:25], 0, v[0:1]
	global_store_dwordx4 v[24:25], v[2:5], off
	v_lshlrev_b32_e32 v0, 1, v14
	s_nop 0
	v_cvt_pk_bf16_f32 v2, v2, v3
	v_cvt_pk_bf16_f32 v3, v4, v5
	s_and_saveexec_b64 s[22:23], s[38:39]
	s_xor_b64 s[38:39], exec, s[22:23]
	s_cbranch_execz .LBB0_1282
	v_lshlrev_b64 v[4:5], 9, v[12:13]
	v_mov_b32_e32 v12, s79
	v_mov_b32_e32 v13, s4
	v_cndmask_b32_e32 v13, v12, v13, vcc
	v_mov_b32_e32 v12, s78
	v_mov_b32_e32 v14, s33
	v_cndmask_b32_e32 v12, v12, v14, vcc
	v_lshl_add_u64 v[4:5], v[4:5], 1, v[12:13]
	v_lshl_add_u64 v[4:5], v[4:5], 0, v[0:1]
	global_store_dwordx2 v[4:5], v[2:3], off
